# s5_setup Kt loop: v_pk_fma_f32 with split real/imag accumulators (1 VALU per complex MAC term instead of 3)
# baseline (speedup 1.0000x reference)
.LBB0_660:
	s_or_b64 exec, exec, s[30:31]
	v_ashrrev_i32_e32 v0, 4, v20
	v_readlane_b32 s2, v255, 5
	v_mov_b32_e32 v2, 0
	v_lshl_add_u32 v22, v0, 3, 0
	v_lshl_add_u32 v21, v18, 9, s2
	s_add_i32 s2, 0, 0x4200
	s_mov_b32 s4, 0
	v_mov_b32_e32 v3, v2
	v_mov_b32_e32 v4, v2
	v_mov_b32_e32 v5, v2
	v_mov_b32_e32 v14, v2
	v_mov_b32_e32 v15, v2
	v_mov_b32_e32 v16, v2
	v_mov_b32_e32 v17, v2
	v_mov_b32_e32 v10, v2
	v_mov_b32_e32 v11, v2
	v_mov_b32_e32 v12, v2
	v_mov_b32_e32 v13, v2
	v_mov_b32_e32 v6, v2
	v_mov_b32_e32 v7, v2
	v_mov_b32_e32 v8, v2
	v_mov_b32_e32 v9, v2
	s_waitcnt lgkmcnt(0)
	s_barrier
	v_mov_b32_e32 v152, 0
	v_mov_b32_e32 v153, 0
	v_mov_b32_e32 v154, 0
	v_mov_b32_e32 v155, 0
	v_mov_b32_e32 v156, 0
	v_mov_b32_e32 v157, 0
	v_mov_b32_e32 v158, 0
	v_mov_b32_e32 v159, 0
	v_mov_b32_e32 v160, 0
	v_mov_b32_e32 v161, 0
	v_mov_b32_e32 v162, 0
	v_mov_b32_e32 v163, 0
	v_mov_b32_e32 v164, 0
	v_mov_b32_e32 v165, 0
	v_mov_b32_e32 v166, 0
	v_mov_b32_e32 v167, 0
	v_mov_b32_e32 v236, 0
	v_mov_b32_e32 v237, 0
	v_mov_b32_e32 v238, 0
	v_mov_b32_e32 v239, 0
	v_mov_b32_e32 v240, 0
	v_mov_b32_e32 v241, 0
	v_mov_b32_e32 v242, 0
	v_mov_b32_e32 v243, 0
	v_mov_b32_e32 v244, 0
	v_mov_b32_e32 v245, 0
	v_mov_b32_e32 v246, 0
	v_mov_b32_e32 v247, 0
	v_mov_b32_e32 v248, 0
	v_mov_b32_e32 v249, 0
	v_mov_b32_e32 v250, 0
	v_mov_b32_e32 v251, 0
	v_add_u32_e32 v23, s4, v21
	ds_read_b128 v[24:27], v23
	ds_read2_b64 v[28:31], v22 offset1:33
	v_mov_b32_e32 v23, s2
	ds_read_b128 v[32:35], v23
	ds_read_b128 v[36:39], v23 offset:16
	ds_read_b128 v[40:43], v23 offset:32
	ds_read_b128 v[44:47], v23 offset:48
	ds_read_b128 v[48:51], v23 offset:64
	ds_read_b128 v[52:55], v23 offset:80
	ds_read_b128 v[56:59], v23 offset:96
	ds_read_b128 v[60:63], v23 offset:112
	ds_read_b128 v[64:67], v23 offset:128
	ds_read_b128 v[68:71], v23 offset:144
	ds_read_b128 v[72:75], v23 offset:160
	ds_read_b128 v[76:79], v23 offset:176
	s_waitcnt lgkmcnt(14)
	ds_read_b128 v[80:83], v23 offset:192
	ds_read_b128 v[84:87], v23 offset:208
	ds_read_b128 v[88:91], v23 offset:224
	ds_read_b128 v[92:95], v23 offset:240
	s_add_i32 s4, s4, 16
	s_addk_i32 s2, 0x100
	v_add_u32_e32 v22, 0x210, v22
.Lkt_loop:
	v_add_u32_e32 v23, s4, v21
	ds_read_b128 v[96:99], v23
	ds_read2_b64 v[100:103], v22 offset1:33
	v_mov_b32_e32 v23, s2
	ds_read_b128 v[120:123], v23
	ds_read_b128 v[124:127], v23 offset:16
	ds_read_b128 v[128:131], v23 offset:32
	ds_read_b128 v[132:135], v23 offset:48
	ds_read_b128 v[136:139], v23 offset:64
	ds_read_b128 v[140:143], v23 offset:80
	ds_read_b128 v[144:147], v23 offset:96
	ds_read_b128 v[148:151], v23 offset:112
	ds_read_b128 v[180:183], v23 offset:128
	ds_read_b128 v[184:187], v23 offset:144
	ds_read_b128 v[188:191], v23 offset:160
	ds_read_b128 v[192:195], v23 offset:176
	s_waitcnt lgkmcnt(14)
	ds_read_b128 v[196:199], v23 offset:192
	ds_read_b128 v[200:203], v23 offset:208
	ds_read_b128 v[204:207], v23 offset:224
	ds_read_b128 v[208:211], v23 offset:240
	s_add_i32 s4, s4, 16
	s_addk_i32 s2, 0x100
	v_add_u32_e32 v22, 0x210, v22
	v_mul_f32_e32 v108, v24, v28
	v_mul_f32_e32 v109, v25, v29
	v_mul_f32_e32 v110, v25, v28
	v_mul_f32_e32 v111, v24, v29
	v_sub_f32_e32 v104, v108, v109
	v_add_f32_e32 v105, v110, v111
	v_xor_b32_e32 v105, 0x80000000, v105
	v_pk_fma_f32 v[152:153], v[32:33], v[104:105], v[152:153]
	v_pk_fma_f32 v[154:155], v[34:35], v[104:105], v[154:155]
	v_pk_fma_f32 v[156:157], v[36:37], v[104:105], v[156:157]
	v_pk_fma_f32 v[158:159], v[38:39], v[104:105], v[158:159]
	v_pk_fma_f32 v[160:161], v[40:41], v[104:105], v[160:161]
	v_pk_fma_f32 v[162:163], v[42:43], v[104:105], v[162:163]
	v_pk_fma_f32 v[164:165], v[44:45], v[104:105], v[164:165]
	v_pk_fma_f32 v[166:167], v[46:47], v[104:105], v[166:167]
	v_pk_fma_f32 v[236:237], v[48:49], v[104:105], v[236:237]
	v_pk_fma_f32 v[238:239], v[50:51], v[104:105], v[238:239]
	v_pk_fma_f32 v[240:241], v[52:53], v[104:105], v[240:241]
	v_pk_fma_f32 v[242:243], v[54:55], v[104:105], v[242:243]
	v_pk_fma_f32 v[244:245], v[56:57], v[104:105], v[244:245]
	v_pk_fma_f32 v[246:247], v[58:59], v[104:105], v[246:247]
	v_pk_fma_f32 v[248:249], v[60:61], v[104:105], v[248:249]
	v_pk_fma_f32 v[250:251], v[62:63], v[104:105], v[250:251]
	v_mul_f32_e32 v108, v26, v30
	v_mul_f32_e32 v109, v27, v31
	v_mul_f32_e32 v110, v27, v30
	v_mul_f32_e32 v111, v26, v31
	v_sub_f32_e32 v106, v108, v109
	v_add_f32_e32 v107, v110, v111
	v_xor_b32_e32 v107, 0x80000000, v107
	v_pk_fma_f32 v[152:153], v[64:65], v[106:107], v[152:153]
	v_pk_fma_f32 v[154:155], v[66:67], v[106:107], v[154:155]
	v_pk_fma_f32 v[156:157], v[68:69], v[106:107], v[156:157]
	v_pk_fma_f32 v[158:159], v[70:71], v[106:107], v[158:159]
	v_pk_fma_f32 v[160:161], v[72:73], v[106:107], v[160:161]
	v_pk_fma_f32 v[162:163], v[74:75], v[106:107], v[162:163]
	v_pk_fma_f32 v[164:165], v[76:77], v[106:107], v[164:165]
	v_pk_fma_f32 v[166:167], v[78:79], v[106:107], v[166:167]
	v_pk_fma_f32 v[236:237], v[80:81], v[106:107], v[236:237]
	v_pk_fma_f32 v[238:239], v[82:83], v[106:107], v[238:239]
	v_pk_fma_f32 v[240:241], v[84:85], v[106:107], v[240:241]
	v_pk_fma_f32 v[242:243], v[86:87], v[106:107], v[242:243]
	v_pk_fma_f32 v[244:245], v[88:89], v[106:107], v[244:245]
	v_pk_fma_f32 v[246:247], v[90:91], v[106:107], v[246:247]
	v_pk_fma_f32 v[248:249], v[92:93], v[106:107], v[248:249]
	v_pk_fma_f32 v[250:251], v[94:95], v[106:107], v[250:251]
	v_add_u32_e32 v23, s4, v21
	ds_read_b128 v[24:27], v23
	ds_read2_b64 v[28:31], v22 offset1:33
	v_mov_b32_e32 v23, s2
	ds_read_b128 v[32:35], v23
	ds_read_b128 v[36:39], v23 offset:16
	ds_read_b128 v[40:43], v23 offset:32
	ds_read_b128 v[44:47], v23 offset:48
	ds_read_b128 v[48:51], v23 offset:64
	ds_read_b128 v[52:55], v23 offset:80
	ds_read_b128 v[56:59], v23 offset:96
	ds_read_b128 v[60:63], v23 offset:112
	ds_read_b128 v[64:67], v23 offset:128
	ds_read_b128 v[68:71], v23 offset:144
	ds_read_b128 v[72:75], v23 offset:160
	ds_read_b128 v[76:79], v23 offset:176
	s_waitcnt lgkmcnt(14)
	ds_read_b128 v[80:83], v23 offset:192
	ds_read_b128 v[84:87], v23 offset:208
	ds_read_b128 v[88:91], v23 offset:224
	ds_read_b128 v[92:95], v23 offset:240
	s_add_i32 s4, s4, 16
	s_addk_i32 s2, 0x100
	v_add_u32_e32 v22, 0x210, v22
	v_mul_f32_e32 v108, v96, v100
	v_mul_f32_e32 v109, v97, v101
	v_mul_f32_e32 v110, v97, v100
	v_mul_f32_e32 v111, v96, v101
	v_sub_f32_e32 v104, v108, v109
	v_add_f32_e32 v105, v110, v111
	v_xor_b32_e32 v105, 0x80000000, v105
	v_pk_fma_f32 v[152:153], v[120:121], v[104:105], v[152:153]
	v_pk_fma_f32 v[154:155], v[122:123], v[104:105], v[154:155]
	v_pk_fma_f32 v[156:157], v[124:125], v[104:105], v[156:157]
	v_pk_fma_f32 v[158:159], v[126:127], v[104:105], v[158:159]
	v_pk_fma_f32 v[160:161], v[128:129], v[104:105], v[160:161]
	v_pk_fma_f32 v[162:163], v[130:131], v[104:105], v[162:163]
	v_pk_fma_f32 v[164:165], v[132:133], v[104:105], v[164:165]
	v_pk_fma_f32 v[166:167], v[134:135], v[104:105], v[166:167]
	v_pk_fma_f32 v[236:237], v[136:137], v[104:105], v[236:237]
	v_pk_fma_f32 v[238:239], v[138:139], v[104:105], v[238:239]
	v_pk_fma_f32 v[240:241], v[140:141], v[104:105], v[240:241]
	v_pk_fma_f32 v[242:243], v[142:143], v[104:105], v[242:243]
	v_pk_fma_f32 v[244:245], v[144:145], v[104:105], v[244:245]
	v_pk_fma_f32 v[246:247], v[146:147], v[104:105], v[246:247]
	v_pk_fma_f32 v[248:249], v[148:149], v[104:105], v[248:249]
	v_pk_fma_f32 v[250:251], v[150:151], v[104:105], v[250:251]
	v_mul_f32_e32 v108, v98, v102
	v_mul_f32_e32 v109, v99, v103
	v_mul_f32_e32 v110, v99, v102
	v_mul_f32_e32 v111, v98, v103
	v_sub_f32_e32 v106, v108, v109
	v_add_f32_e32 v107, v110, v111
	v_xor_b32_e32 v107, 0x80000000, v107
	v_pk_fma_f32 v[152:153], v[180:181], v[106:107], v[152:153]
	v_pk_fma_f32 v[154:155], v[182:183], v[106:107], v[154:155]
	v_pk_fma_f32 v[156:157], v[184:185], v[106:107], v[156:157]
	v_pk_fma_f32 v[158:159], v[186:187], v[106:107], v[158:159]
	v_pk_fma_f32 v[160:161], v[188:189], v[106:107], v[160:161]
	v_pk_fma_f32 v[162:163], v[190:191], v[106:107], v[162:163]
	v_pk_fma_f32 v[164:165], v[192:193], v[106:107], v[164:165]
	v_pk_fma_f32 v[166:167], v[194:195], v[106:107], v[166:167]
	v_pk_fma_f32 v[236:237], v[196:197], v[106:107], v[236:237]
	v_pk_fma_f32 v[238:239], v[198:199], v[106:107], v[238:239]
	v_pk_fma_f32 v[240:241], v[200:201], v[106:107], v[240:241]
	v_pk_fma_f32 v[242:243], v[202:203], v[106:107], v[242:243]
	v_pk_fma_f32 v[244:245], v[204:205], v[106:107], v[244:245]
	v_pk_fma_f32 v[246:247], v[206:207], v[106:107], v[246:247]
	v_pk_fma_f32 v[248:249], v[208:209], v[106:107], v[248:249]
	v_pk_fma_f32 v[250:251], v[210:211], v[106:107], v[250:251]
	s_cmpk_lg_i32 s4, 0x210
	s_cbranch_scc1 .Lkt_loop
	s_waitcnt lgkmcnt(0)
	v_add_f32_e32 v2, v152, v153
	v_add_f32_e32 v3, v154, v155
	v_add_f32_e32 v4, v156, v157
	v_add_f32_e32 v5, v158, v159
	v_add_f32_e32 v14, v160, v161
	v_add_f32_e32 v15, v162, v163
	v_add_f32_e32 v16, v164, v165
	v_add_f32_e32 v17, v166, v167
	v_add_f32_e32 v10, v236, v237
	v_add_f32_e32 v11, v238, v239
	v_add_f32_e32 v12, v240, v241
	v_add_f32_e32 v13, v242, v243
	v_add_f32_e32 v6, v244, v245
	v_add_f32_e32 v7, v246, v247
	v_add_f32_e32 v8, v248, v249
	v_add_f32_e32 v9, v250, v251
	v_mul_lo_u32 v0, v0, s37
	v_lshlrev_b32_e32 v18, 6, v18
	s_lshl_b32 s2, s36, 9
	v_add3_u32 v0, 0, v0, v18
	s_and_b32 s2, s2, 0x200
	ds_write_b128 v0, v[2:5] offset:33280
	ds_write_b128 v0, v[14:17] offset:33296
	ds_write_b128 v0, v[10:13] offset:33312
	ds_write_b128 v0, v[6:9] offset:33328
	v_add_u32_e32 v2, s2, v20
	s_movk_i32 s2, 0x4000
	v_cmp_gt_i32_e32 vcc, s2, v2
	s_waitcnt lgkmcnt(0)
	s_barrier
	s_and_saveexec_b64 s[4:5], vcc
	s_cbranch_execz .LBB0_667
	s_mov_b32 s11, s51
	s_lshl_b64 s[2:3], s[10:11], 18
	s_add_u32 s2, s12, s2
	v_and_b32_e32 v0, 63, v19
	s_addc_u32 s3, s13, s3
	v_lshlrev_b32_e32 v0, 4, v0
	v_bfe_u32 v3, v19, 1, 5
	v_lshl_add_u64 v[4:5], s[2:3], 0, v[0:1]
	s_mov_b64 s[2:3], 0xa500000
	v_xor_b32_e32 v3, 31, v3
	v_lshl_add_u64 v[4:5], v[4:5], 0, s[2:3]
	v_lshlrev_b32_e32 v0, 6, v2
	s_mov_b64 s[6:7], 0
	v_mov_b32_e32 v8, v2
	s_branch .LBB0_665
